# v40 lineage with the whole layer-0 gate/up weight copy in the cross-attention q-projection idle slot (XQF_N 22016), none in the prologue
# speedup vs baseline: 1.0020x; 1.0020x over previous
.LBB0_680:
	s_lshr_b32 s11, s54, 6
	s_cmpk_lt_i32 s95, 0x700
	s_cselect_b64 s[0:1], -1, 0
	v_writelane_b32 v252, s0, 9
	s_ashr_i32 s81, s95, 31
	s_ashr_i32 s14, s97, 31
	v_writelane_b32 v252, s1, 10
	s_lshr_b32 s0, s81, 29
	s_add_i32 s12, s95, s0
	s_and_b32 s1, s12, -8
	s_ashr_i32 s0, s12, 3
	s_sub_i32 s1, s95, s1
	v_readlane_b32 s16, v251, 2
	v_readlane_b32 s17, v251, 3
	s_add_u32 s2, s16, 0x4200
	s_addc_u32 s3, s17, 0
	v_writelane_b32 v251, s2, 63
	s_lshl_b32 s87, s55, 8
	v_readlane_b32 s36, v251, 16
	v_writelane_b32 v252, s3, 0
	s_add_u32 s2, s56, s87
	s_addc_u32 s3, s57, 0
	s_add_u32 s4, s2, 0x1400
	s_addc_u32 s5, s3, 0
	v_writelane_b32 v252, s4, 11
	s_add_u32 s2, s2, 0x2400
	s_addc_u32 s3, s3, 0
	v_writelane_b32 v252, s5, 12
	v_writelane_b32 v252, s2, 13
	v_readlane_b32 s44, v251, 24
	v_readlane_b32 s45, v251, 25
	v_writelane_b32 v252, s3, 14
	s_add_u32 s2, s16, 0x7400
	s_addc_u32 s3, s17, 0
	v_writelane_b32 v252, s2, 15
	s_mov_b32 s77, 0
	v_readlane_b32 s42, v251, 22
	v_writelane_b32 v252, s3, 16
	s_add_u32 s2, s16, 0x7500
	s_addc_u32 s3, s17, 0
	v_writelane_b32 v252, s2, 17
	s_cmp_lt_i32 s95, 64
	v_readlane_b32 s43, v251, 23
	v_writelane_b32 v252, s3, 18
	s_cselect_b64 s[2:3], -1, 0
	s_lshl_b32 s9, s1, 3
	v_writelane_b32 v252, s2, 19
	s_cmp_gt_i32 s95, 63
	v_readlane_b32 s50, v251, 30
	v_writelane_b32 v252, s3, 20
	s_cselect_b64 s[2:3], -1, 0
	v_writelane_b32 v252, s2, 21
	v_readlane_b32 s51, v251, 31
	v_readlane_b32 s18, v251, 50
	v_writelane_b32 v252, s3, 22
	s_sub_i32 s2, s95, 64
	s_cmp_lt_u32 s2, 64
	v_writelane_b32 v252, s2, 23
	s_cselect_b64 s[2:3], -1, 0
	s_lshl_b32 s19, s95, 3
	s_and_b32 s7, s19, 56
	s_bfe_u32 s8, s95, 0x30003
	v_writelane_b32 v252, s2, 24
	s_cmpk_eq_i32 s97, 0x100
	v_readlane_b32 s37, v251, 17
	v_writelane_b32 v252, s3, 25
	s_cselect_b64 s[2:3], -1, 0
	s_and_b64 s[4:5], s[2:3], exec
	s_cselect_b32 s6, 0x80, 0
	s_sub_i32 s4, s97, s6
	s_cmp_ge_i32 s95, s6
	s_cselect_b64 s[20:21], -1, 0
	v_writelane_b32 v252, s20, 26
	s_mul_i32 s5, s11, 0x2100
	s_add_i32 s5, s5, 0
	v_writelane_b32 v252, s21, 27
	v_writelane_b32 v252, s5, 28
	s_sub_i32 s5, s95, s6
	s_lshl_b32 s5, s5, 3
	s_add_i32 s28, s5, s11
	s_cmpk_lt_i32 s28, 0x4800
	s_cselect_b64 s[20:21], -1, 0
	v_writelane_b32 v252, s20, 29
	v_readlane_b32 s38, v251, 18
	v_readlane_b32 s39, v251, 19
	v_writelane_b32 v252, s21, 30
	v_readlane_b32 s20, v251, 8
	v_readlane_b32 s22, v251, 10
	v_readlane_b32 s23, v251, 11
	s_add_u32 s22, s22, 0x15800000
	s_addc_u32 s23, s23, 0
	s_add_u32 s70, s44, 0x8000
	v_writelane_b32 v252, s22, 5
	s_addc_u32 s71, s45, 0
	s_lshl_b32 s4, s4, 3
	v_writelane_b32 v252, s23, 6
	s_cmp_lt_i32 s95, 32
	v_writelane_b32 v252, s4, 31
	s_cselect_b64 s[4:5], -1, 0
	v_writelane_b32 v252, s4, 32
	s_lshl_b32 s10, s1, 2
	v_readlane_b32 s21, v251, 9
	v_writelane_b32 v252, s5, 33
	s_add_u32 s4, s16, 0x1000
	s_addc_u32 s5, s17, 0
	v_writelane_b32 v252, s4, 34
	s_cmpk_lt_i32 s95, 0x800
	v_readlane_b32 s24, v251, 12
	v_writelane_b32 v252, s5, 35
	s_cselect_b64 s[4:5], -1, 0
	v_writelane_b32 v252, s4, 36
	s_and_b32 s13, s1, 3
	s_add_i32 s76, s1, 32
	v_writelane_b32 v252, s5, 37
	s_lshl_b32 s5, s12, 2
	s_and_b32 s12, s5, 0xffffffe0
	s_ashr_i32 s4, s1, 2
	s_sub_i32 s15, 0x1fe0, s12
	s_ashr_i32 s5, s4, 31
	v_writelane_b32 v252, s15, 38
	s_ashr_i32 s15, s15, 31
	v_writelane_b32 v252, s15, 39
	s_lshl_b64 s[4:5], s[4:5], 26
	v_writelane_b32 v252, s4, 40
	s_add_i32 s22, s11, s19
	v_readlane_b32 s25, v251, 13
	v_writelane_b32 v252, s5, 41
	s_lshl_b32 s4, s13, 10
	v_writelane_b32 v252, s4, 42
	s_lshl_b64 s[4:5], s[76:77], 21
	v_writelane_b32 v252, s4, 43
	v_readlane_b32 s26, v251, 14
	v_readlane_b32 s27, v251, 15
	v_writelane_b32 v252, s5, 44
	s_sub_i32 s4, 0x1de1, s12
	s_max_i32 s4, s4, 0
	s_and_b32 s76, s4, 0x7fffffc0
	s_lshl_b64 s[4:5], s[76:77], 8
	v_writelane_b32 v252, s4, 45
	v_readlane_b32 s40, v251, 20
	v_readlane_b32 s41, v251, 21
	v_writelane_b32 v252, s5, 46
	s_add_u32 s4, s20, 0x800000
	s_addc_u32 s5, s21, 0
	v_writelane_b32 v252, s4, 47
	v_readlane_b32 s46, v251, 26
	v_readlane_b32 s47, v251, 27
	v_writelane_b32 v252, s5, 48
	s_mov_b64 s[4:5], s[52:53]
	v_readlane_b32 s52, v251, 32
	v_readlane_b32 s64, v251, 44
	v_readlane_b32 s65, v251, 45
	s_mov_b64 s[24:25], s[64:65]
	s_mov_b64 s[64:65], s[4:5]
	s_add_u32 s4, s24, 0x800000
	s_addc_u32 s5, s25, 0
	v_writelane_b32 v252, s4, 49
	v_readlane_b32 s67, v251, 47
	s_mov_b32 s67, s14
	v_writelane_b32 v252, s5, 50
	s_add_u32 s4, s42, 0x8000
	s_addc_u32 s5, s43, 0
	s_lshl_b32 s90, s97, 3
	v_writelane_b32 v252, s4, 51
	s_cmpk_lt_i32 s95, 0x400
	v_readlane_b32 s56, v251, 36
	v_writelane_b32 v252, s5, 52
	s_cselect_b64 s[4:5], -1, 0
	v_writelane_b32 v252, s4, 53
	v_readlane_b32 s57, v251, 37
	v_readlane_b32 s58, v251, 38
	v_writelane_b32 v252, s5, 54
	s_ashr_i32 s4, s95, 4
	s_lshl_b32 s5, s95, 1
	s_and_b32 s4, s4, -16
	s_and_b32 s5, s5, 12
	s_or_b32 s4, s4, s5
	s_bfe_u32 s5, s95, 0x20006
	s_or_b32 s20, s4, s5
	s_and_b32 s4, s19, 8
	s_or_b32 s23, s4, s8
	s_mov_b64 s[4:5], 0
	v_writelane_b32 v252, s4, 55
	s_cmp_lg_u64 s[50:51], 0
	v_readlane_b32 s59, v251, 39
	v_writelane_b32 v252, s5, 56
	s_cselect_b64 s[4:5], -1, 0
	v_writelane_b32 v252, s4, 57
	s_cmp_gt_i32 s65, 3
	v_readlane_b32 s48, v251, 28
	v_writelane_b32 v252, s5, 58
	s_cselect_b64 s[4:5], -1, 0
	v_writelane_b32 v252, s4, 59
	s_cmpk_gt_i32 s97, 0xff
	v_readlane_b32 s49, v251, 29
	v_writelane_b32 v252, s5, 60
	s_cselect_b64 s[4:5], -1, 0
	v_writelane_b32 v252, s4, 61
	s_cmpk_lt_i32 s95, 0x80
	v_readlane_b32 s53, v251, 33
	v_writelane_b32 v252, s5, 62
	s_cselect_b64 s[4:5], -1, 0
	s_lshl_b32 s14, s1, 4
	v_writelane_b32 v252, s4, 63
	s_cmpk_lt_u32 s95, 0x100
	v_readlane_b32 s54, v251, 34
	v_writelane_b32 v253, s5, 0
	s_cselect_b64 s[4:5], -1, 0
	v_writelane_b32 v253, s4, 1
	s_lshr_b32 s11, s95, 5
	s_or_b32 s12, s7, s11
	v_writelane_b32 v253, s5, 2
	s_bfe_u32 s4, s95, 0x10003
	s_lshl_b32 s13, s12, 21
	s_lshl_b32 s25, s4, 20
	s_lshl_b32 s12, s12, 8
	s_lshl_b32 s4, s4, 7
	s_bfe_u32 s5, s95, 0x10004
	v_writelane_b32 v253, s13, 3
	s_or_b32 s4, s12, s4
	s_lshl_b32 s24, s5, 21
	v_writelane_b32 v253, s4, 4
	s_lshl_b32 s4, s5, 8
	s_cmpk_gt_i32 s95, 0x7f
	v_writelane_b32 v253, s4, 5
	s_cselect_b64 s[4:5], -1, 0
	v_writelane_b32 v253, s4, 6
	v_readlane_b32 s55, v251, 35
	v_readlane_b32 s60, v251, 40
	v_writelane_b32 v253, s5, 7
	s_add_i32 s5, s95, 0xffffff80
	s_cmp_lt_u32 s5, 16
	s_cselect_b64 s[12:13], -1, 0
	s_add_i32 s4, s95, 0x78
	v_writelane_b32 v253, s12, 8
	s_cmp_lt_u32 s5, 8
	v_readlane_b32 s61, v251, 41
	v_writelane_b32 v253, s13, 9
	s_cselect_b32 s12, s95, s4
	s_cmp_gt_u32 s5, 7
	v_writelane_b32 v253, s5, 10
	s_cselect_b64 s[4:5], -1, 0
	s_and_b32 s15, s12, 0x7f
	s_and_b64 s[12:13], s[4:5], exec
	s_cselect_b32 s12, 0x200000, 0
	v_writelane_b32 v253, s12, 11
	v_writelane_b32 v253, s15, 12
	s_lshl_b32 s12, s15, 21
	v_writelane_b32 v253, s12, 13
	s_add_i32 s12, s18, 0xfffec000
	s_cmpk_gt_i32 s95, 0x8f
	v_writelane_b32 v253, s12, 14
	s_cselect_b64 s[12:13], -1, 0
	s_and_b64 s[2:3], s[12:13], s[2:3]
	v_writelane_b32 v253, s2, 15
	v_cndmask_b32_e64 v226, 0, 1, s[4:5]
	s_movk_i32 s4, 0xe1
	v_writelane_b32 v253, s3, 16
	s_add_i32 s2, s22, 0xfffffb80
	s_cmpk_lt_i32 s2, 0x5600
	s_cselect_b64 s[2:3], -1, 0
	v_writelane_b32 v253, s2, 17
	s_cmp_lg_u64 s[44:45], 0
	s_mul_i32 s12, s1, 17
	v_writelane_b32 v253, s3, 18
	s_cselect_b64 s[2:3], -1, 0
	v_writelane_b32 v253, s2, 19
	s_cmpk_lt_i32 s95, 0x100
	v_readlane_b32 s62, v251, 42
	v_writelane_b32 v253, s3, 20
	s_cselect_b64 s[2:3], -1, 0
	v_writelane_b32 v253, s2, 21
	s_cmpk_lt_i32 s95, 0x1580
	v_readlane_b32 s63, v251, 43
	v_writelane_b32 v253, s3, 22
	s_cselect_b64 s[2:3], -1, 0
	v_writelane_b32 v253, s2, 23
	s_cmpk_lt_i32 s28, 0x2b00
	v_readlane_b32 s66, v251, 46
	v_writelane_b32 v253, s3, 24
	s_cselect_b64 s[2:3], -1, 0
	v_writelane_b32 v253, s2, 25
	s_cmp_lt_i32 s1, 0
	s_cselect_b32 s4, s4, 0xe0
	v_writelane_b32 v253, s3, 26
	v_cmp_eq_u32_e64 s[2:3], 0, v0
	s_mul_i32 s4, s1, s4
	v_mov_b32_e32 v145, 0
	v_writelane_b32 v253, s2, 27
	s_mov_b64 s[88:89], 0x80
	s_movk_i32 s60, 0xf000
	v_writelane_b32 v253, s3, 28
	s_mul_i32 s2, s1, 9
	s_mul_i32 s3, s1, 5
	s_cselect_b32 s5, s2, s9
	s_movk_i32 s2, 0x2b1
	s_cselect_b32 s3, s3, s10
	s_cselect_b32 s9, s12, s14
	s_cselect_b32 s14, s2, 0x2b0
	s_add_i32 s4, s4, s0
	s_mul_hi_i32 s2, s4, 0x92492493
	s_add_i32 s2, s2, s4
	s_lshr_b32 s10, s2, 31
	s_ashr_i32 s2, s2, 7
	s_add_i32 s2, s2, s10
	s_mul_i32 s10, s2, 0xe0
	s_sub_i32 s4, s4, s10
	s_lshl_b32 s12, s2, 3
	s_bfe_u32 s2, s4, 0x3001c
	s_add_i32 s10, s4, s2
	s_sext_i32_i16 s13, s10
	s_and_b32 s10, s10, 0xfff8
	s_sub_i32 s4, s4, s10
	s_sext_i32_i16 s4, s4
	s_add_i32 s26, s12, s4
	s_ashr_i32 s4, s13, 3
	v_writelane_b32 v253, s4, 29
	s_add_i32 s4, s5, s0
	s_ashr_i32 s5, s4, 31
	s_lshr_b32 s5, s5, 27
	s_add_i32 s5, s4, s5
	s_ashr_i32 s10, s5, 5
	s_and_b32 s5, s5, 0xffe0
	s_sub_i32 s5, s4, s5
	s_bfe_i32 s4, s5, 0x80000
	s_lshr_b32 s12, s4, 7
	s_bfe_u32 s4, s12, 0x30005
	s_lshr_b32 s2, s13, 3
	s_add_i32 s13, s5, s4
	s_bfe_i32 s4, s13, 0x80000
	s_and_b32 s13, s13, 0xf8
	s_sub_i32 s13, s5, s13
	s_lshl_b32 s10, s10, 3
	s_sext_i32_i16 s15, s4
	s_sext_i32_i8 s13, s13
	s_add_i32 s30, s10, s13
	s_ashr_i32 s10, s15, 3
	v_writelane_b32 v253, s10, 30
	s_bfe_u32 s10, s12, 0x40004
	s_add_i32 s5, s5, s10
	s_bfe_i32 s5, s5, 0x80000
	s_sext_i32_i16 s5, s5
	s_lshr_b32 s10, s5, 4
	s_bfe_i64 s[12:13], s[10:11], 0x100000
	s_mov_b32 s10, s30
	s_ashr_i32 s31, s30, 31
	v_writelane_b32 v253, s10, 31
	s_lshr_b32 s4, s15, 3
	s_lshl_b64 s[30:31], s[30:31], 20
	v_writelane_b32 v253, s11, 32
	v_writelane_b32 v253, s30, 33
	s_bfe_i64 s[4:5], s[4:5], 0x100000
	s_lshl_b64 s[4:5], s[4:5], 21
	v_writelane_b32 v253, s31, 34
	v_writelane_b32 v253, s4, 35
	s_add_i32 s3, s3, s0
	s_ashr_i32 s21, s20, 31
	v_writelane_b32 v253, s5, 36
	s_lshl_b64 s[4:5], s[12:13], 24
	v_writelane_b32 v253, s4, 37
	s_mul_i32 s1, s1, s14
	s_add_i32 s1, s1, s0
	v_writelane_b32 v253, s5, 38
	s_or_b32 s4, s7, s8
	v_writelane_b32 v253, s4, 39
	s_lshl_b32 s4, s4, 21
	v_writelane_b32 v253, s4, 40
	s_ashr_i32 s4, s3, 31
	s_lshr_b32 s4, s4, 28
	s_add_i32 s4, s3, s4
	s_ashr_i32 s5, s4, 4
	s_and_b32 s4, s4, 0xfff0
	s_sub_i32 s3, s3, s4
	s_bfe_i32 s4, s3, 0x80000
	s_bfe_u32 s4, s4, 0x3000c
	s_add_i32 s7, s3, s4
	s_bfe_i32 s4, s7, 0x80000
	s_and_b32 s7, s7, 0xf8
	s_sub_i32 s3, s3, s7
	s_lshl_b32 s5, s5, 3
	s_sext_i32_i16 s8, s4
	s_sext_i32_i8 s3, s3
	s_add_i32 s12, s5, s3
	s_ashr_i32 s3, s8, 3
	s_lshr_b32 s4, s8, 3
	v_writelane_b32 v253, s3, 41
	s_mov_b32 s8, s12
	s_ashr_i32 s13, s12, 31
	v_writelane_b32 v253, s8, 42
	s_lshl_b64 s[12:13], s[12:13], 18
	s_bfe_i64 s[4:5], s[4:5], 0x100000
	v_writelane_b32 v253, s9, 43
	v_writelane_b32 v253, s12, 44
	s_lshl_b32 s3, s23, 21
	s_ashr_i32 s27, s26, 31
	v_writelane_b32 v253, s13, 45
	s_lshl_b64 s[12:13], s[4:5], 18
	v_writelane_b32 v253, s12, 46
	s_lshl_b64 s[4:5], s[4:5], 22
	v_mov_b32_e32 v227, 1
	v_writelane_b32 v253, s13, 47
	v_writelane_b32 v253, s4, 48
	s_movk_i32 s86, 0x70
	s_movk_i32 s82, 0xfdff
	v_writelane_b32 v253, s5, 49
	s_lshl_b64 s[4:5], s[20:21], 21
	v_writelane_b32 v253, s4, 50
	s_mov_b32 s78, 0x3e0293ee
	s_mov_b32 s83, 0x41380000
	v_writelane_b32 v253, s5, 51
	v_writelane_b32 v253, s3, 52
	s_lshl_b32 s3, s23, 9
	s_and_b32 s3, s3, 0x1800
	v_writelane_b32 v253, s3, 53
	s_lshl_b32 s3, s23, 19
	v_writelane_b32 v253, s3, 54
	s_add_i32 s3, s9, s0
	s_ashr_i32 s4, s3, 31
	s_lshr_b32 s4, s4, 28
	s_add_i32 s4, s3, s4
	s_ashr_i32 s5, s4, 4
	s_and_b32 s4, s4, 0xfff0
	s_sub_i32 s3, s3, s4
	s_bfe_i32 s4, s3, 0x80000
	s_bfe_u32 s4, s4, 0x3000c
	s_add_i32 s7, s3, s4
	s_bfe_i32 s4, s7, 0x80000
	s_and_b32 s7, s7, 0xf8
	s_sub_i32 s3, s3, s7
	s_lshl_b32 s5, s5, 3
	s_sext_i32_i16 s8, s4
	s_sext_i32_i8 s3, s3
	s_add_i32 s12, s5, s3
	s_ashr_i32 s3, s8, 3
	s_lshr_b32 s4, s8, 3
	v_writelane_b32 v253, s3, 55
	s_mov_b32 s8, s12
	s_ashr_i32 s13, s12, 31
	v_writelane_b32 v253, s8, 56
	s_bfe_i64 s[4:5], s[4:5], 0x100000
	s_lshl_b64 s[4:5], s[4:5], 21
	v_writelane_b32 v253, s9, 57
	s_lshl_b64 s[8:9], s[12:13], 21
	v_writelane_b32 v253, s8, 58
	s_lshl_b32 s3, s23, 18
	s_mul_hi_i32 s0, s1, 0x2fa0be83
	v_writelane_b32 v253, s9, 59
	v_writelane_b32 v253, s4, 60
	s_movk_i32 s61, 0xe000
	s_brev_b32 s63, -2
	v_writelane_b32 v253, s5, 61
	s_mov_b32 s4, s20
	v_writelane_b32 v253, s4, 62
	s_brev_b32 s68, 1
	v_mov_b32_e32 v228, 0x358637bd
	v_writelane_b32 v253, s5, 63
	s_lshl_b64 s[4:5], s[20:21], 18
	v_writelane_b32 v254, s4, 0
	s_mov_b32 s38, 0xf800000
	v_mov_b32_e32 v229, 0x260
	v_writelane_b32 v254, s5, 1
	v_writelane_b32 v254, s23, 2
	v_writelane_b32 v254, s3, 3
	s_lshr_b32 s3, s0, 31
	s_ashr_i32 s0, s0, 7
	s_add_i32 s0, s0, s3
	s_lshl_b32 s3, s0, 3
	s_mulk_i32 s0, 0x2b0
	s_sub_i32 s1, s1, s0
	s_bfe_u32 s0, s1, 0x3001c
	s_add_i32 s4, s1, s0
	s_sext_i32_i16 s5, s4
	s_and_b32 s4, s4, 0xfff8
	s_sub_i32 s1, s1, s4
	s_sext_i32_i16 s1, s1
	s_add_i32 s8, s3, s1
	s_ashr_i32 s1, s5, 3
	v_writelane_b32 v254, s1, 4
	s_mov_b32 s4, s26
	s_lshr_b32 s0, s5, 3
	v_writelane_b32 v254, s4, 5
	s_bfe_i64 s[2:3], s[2:3], 0x100000
	s_lshl_b64 s[2:3], s[2:3], 21
	v_writelane_b32 v254, s5, 6
	s_lshl_b64 s[4:5], s[26:27], 21
	v_writelane_b32 v254, s4, 7
	s_ashr_i32 s9, s8, 31
	s_bfe_i64 s[0:1], s[0:1], 0x100000
	v_writelane_b32 v254, s5, 8
	v_writelane_b32 v254, s2, 9
	s_lshl_b64 s[0:1], s[0:1], 21
	s_mov_b64 s[4:5], -1
	v_writelane_b32 v254, s3, 10
	s_mov_b32 s2, s8
	v_writelane_b32 v254, s2, 11
	s_mov_b32 s39, 0xf7fff000
	s_brev_b32 s40, 31
	v_writelane_b32 v254, s3, 12
	s_lshl_b64 s[2:3], s[8:9], 21
	v_writelane_b32 v254, s2, 13
	s_add_u32 s74, s16, 0x4400
	s_addc_u32 s75, s17, 0
	v_writelane_b32 v254, s3, 14
	v_writelane_b32 v254, s0, 15
	s_ashr_i32 s91, s90, 31
	s_lshl_b64 s[56:57], s[90:91], 13
	v_writelane_b32 v254, s1, 16
	v_writelane_b32 v254, s28, 17
	s_lshl_b32 s0, s28, 6
	v_writelane_b32 v254, s0, 18
	s_lshl_b32 s1, s97, 9
	s_lshl_b32 s0, s6, 9
	s_sub_i32 s0, s1, s0
	v_writelane_b32 v254, s0, 19
	v_writelane_b32 v254, s19, 20
	s_ashr_i32 s0, s19, 31
	v_writelane_b32 v252, s1, 3
	v_writelane_b32 v254, s0, 21
	s_lshl_b64 s[0:1], s[90:91], 2
	v_writelane_b32 v252, s0, 1
	s_lshl_b64 s[58:59], s[90:91], 8
	s_movk_i32 s41, 0xd000
	v_writelane_b32 v252, s1, 2
	s_add_u32 s0, s36, 0x3810
	v_writelane_b32 v254, s0, 22
	s_addc_u32 s0, s37, 0
	v_writelane_b32 v254, s0, 23
	s_lshl_b64 s[0:1], s[90:91], 14
	v_writelane_b32 v254, s0, 24
	v_writelane_b32 v252, s56, 7
	v_mov_b32_e32 v230, 0xff800000
	v_writelane_b32 v254, s1, 25
	v_writelane_b32 v254, s24, 26
	s_or_b32 s0, s24, 0x7000100
	v_writelane_b32 v254, s0, 27
	s_and_b32 s0, s95, 7
	s_lshl_b32 s0, s0, 24
	s_lshl_b32 s1, s11, 21
	s_add_i32 s0, s0, s1
	v_writelane_b32 v254, s25, 28
	s_or_b32 s0, s25, s0
	v_writelane_b32 v254, s0, 29
	s_add_u32 s0, s0, 0x29000080
	v_writelane_b32 v254, s0, 30
	s_addc_u32 s0, 0, 0
	v_writelane_b32 v254, s0, 31
	v_writelane_b32 v254, s22, 32
	s_add_i32 s0, s22, 0xfffff800
	v_writelane_b32 v254, s0, 33
	s_add_i32 s0, s18, 0xfffee000
	v_writelane_b32 v254, s0, 34
	v_readlane_b32 s0, v251, 4
	v_readlane_b32 s2, v251, 6
	v_readlane_b32 s1, v251, 5
	v_readlane_b32 s3, v251, 7
	s_add_u32 s0, s2, 0x3810
	v_writelane_b32 v251, s81, 57
	v_writelane_b32 v254, s0, 35
	s_addc_u32 s0, s3, 0
	v_writelane_b32 v251, s67, 56
	v_writelane_b32 v254, s0, 36
	s_add_i32 s2, 0, 0x18400
	v_writelane_b32 v251, s58, 61
	s_movk_i32 s0, 0x5600
	s_mov_b32 s1, 0x15800
	v_writelane_b32 v254, s2, 37
	v_mov_b32_e32 v231, 0x49742401
	v_mov_b64_e32 v[184:185], 0x400
	v_mov_b64_e32 v[186:187], 0x3ff
	v_mov_b64_e32 v[192:193], 0x1580
	v_mov_b64_e32 v[194:195], 0x157f
	s_mov_b32 s44, s77
	v_writelane_b32 v252, s57, 8
	v_writelane_b32 v251, s59, 62
	s_branch .LBB0_684
